# v8 + grid barrier before layer-1 in-proj split: arrive right after w_in_b transposes (group count, last WG writes back L2), panel sync at phase end, WAR guard before in-proj epilogue stores
# speedup vs baseline: 1.0371x; 1.0075x over previous
; __device__ __forceinline__ unsigned xb_ld(unsigned* p)              { return __hip_atomic_load(p, __ATOMIC_RELAXED, __HIP_MEMORY_SCOPE_AGENT); }
; __device__ __forceinline__ unsigned xb_add(unsigned* p, unsigned v) { return __hip_atomic_fetch_add(p, v, __ATOMIC_RELAXED, __HIP_MEMORY_SCOPE_AGENT); }
; #define XB_SPIN(cond, bar) do { unsigned _sp = 0; while (cond) { __builtin_amdgcn_s_sleep(1); \
;     if ((++_sp & 255u) == 0u) { if (xb_ld(&(bar)[XB_TMO])) break; if (_sp > XB_SPIN_CAP) { atomicAdd(&(bar)[XB_TMO], 1u); break; } } } } while (0)
; __device__ __forceinline__ void xcd_barrier(const XcdBarrier& b) {
;     asm volatile("s_waitcnt vmcnt(0)" ::: "memory");
;     __syncthreads();
;     if (threadIdx.x == 0) {
;         unsigned* bar = b.bar;
;         __builtin_amdgcn_s_waitcnt(0);
;         unsigned nloc = b.st[0], nx = b.st[1];
;         if (nloc == 0u) { xcd_barrier_complete(bar, b.x, nloc, nx); b.st[0] = nloc; b.st[1] = nx; }
;         const unsigned old = xb_add(&bar[XB_XSUB(b.x)], 1u);
;         const unsigned gen = old / nloc;
;         if (old + 1u == (gen + 1u) * nloc) {
;             __builtin_amdgcn_fence(__ATOMIC_RELEASE, "agent");
;             asm volatile("s_waitcnt vmcnt(0)" ::: "memory");
;             const unsigned og = xb_add(&bar[XB_TOP], 1u);
;             const unsigned tg = og / nx;
;             if (og + 1u == (tg + 1u) * nx) xb_add(&bar[XB_TOPGEN], 1u);
;             else XB_SPIN(xb_ld(&bar[XB_TOPGEN]) == tg, bar);
;             __builtin_amdgcn_fence(__ATOMIC_ACQUIRE, "agent");
;             xb_add(&bar[XB_XGEN(b.x)], 1u);
;             asm volatile("s_waitcnt vmcnt(0)" ::: "memory");
;         } else {
;             XB_SPIN(xb_ld(&bar[XB_XGEN(b.x)]) == gen, bar);
;             __builtin_amdgcn_fence(__ATOMIC_ACQUIRE, "agent");
;             asm volatile("s_waitcnt vmcnt(0)" ::: "memory");
;         }
;     }
;     __syncthreads();
; }
; __global__ void __launch_bounds__(NTHREADS, 2) mk_fwd(Params P) {
;     ...
;         transpose_convert(lds, P.w_in_b, WINB, 2048, 8192, G, bid);
;         pg8::Gemm g{X1B, WG0, MTOK, 2048, 2048, 1 << 30, 0}; pg8::StaticOrder S; S.init(MTOK, 2048, G, bid);
;         EpiPle<false> E{X1B, PP0, SLOTA, nullptr}; pg8::gemm_phase<EpiPle<false>, true>(lds, g, S, E);
.LBB0_424:
	s_waitcnt vmcnt(0) lgkmcnt(0)
	s_barrier
	s_and_saveexec_b64 s[100:101], s[12:13]
	s_cbranch_execz .Lpw3_done
	s_and_b32 s98, s2, 7
	s_lshl_b32 s98, s98, 6
	s_add_i32 s98, s98, 0x8000
	v_mov_b32_e32 v255, s98
	v_mov_b32_e32 v252, 1
	v_mov_b32_e32 v253, 0x2000c
	ds_read_b32 v254, v253
	s_waitcnt lgkmcnt(0)
	v_readfirstlane_b32 s99, v254
	s_cmp_eq_u32 s99, 1
	s_cbranch_scc1 .Lg5_fast
	buffer_wbl2 sc1
	s_waitcnt vmcnt(0)
.Lg5_fast:
	global_atomic_add v254, v255, v252, s[54:55] offset:16 sc0
	s_and_b32 s98, s2, 7
	s_lshl_b32 s98, s98, 2
	s_bfe_u32 s99, s2, 0x20003
	s_or_b32 s98, s98, s99
	s_lshl_b32 s98, s98, 6
	s_add_i32 s98, s98, 0xa400
	v_mov_b32_e32 v250, s98
	s_mov_b32 s99, 0

; __global__ void __launch_bounds__(NTHREADS, 2) mk_fwd(Params P) {
;     ...
;         transpose_convert(lds, P.w_in_b, WINB, 2048, 8192, G, bid);
;         pg8::Gemm g{X1B, WG0, MTOK, 2048, 2048, 1 << 30, 0}; pg8::StaticOrder S; S.init(MTOK, 2048, G, bid);
;         EpiPle<false> E{X1B, PP0, SLOTA, nullptr}; pg8::gemm_phase<EpiPle<false>, true>(lds, g, S, E);
.Lpw3_ok:
	v_readfirstlane_b32 s98, v254
	s_cmp_eq_u32 s98, 31
	s_cbranch_scc0 .Lg5_notlast
	buffer_wbl2 sc1
	s_waitcnt vmcnt(0)
	v_mov_b32_e32 v255, 0x8200
	global_atomic_add v255, v252, s[54:55]

; __device__ __forceinline__ unsigned xb_ld(unsigned* p)              { return __hip_atomic_load(p, __ATOMIC_RELAXED, __HIP_MEMORY_SCOPE_AGENT); }
; __device__ __forceinline__ unsigned xb_add(unsigned* p, unsigned v) { return __hip_atomic_fetch_add(p, v, __ATOMIC_RELAXED, __HIP_MEMORY_SCOPE_AGENT); }
; #define XB_SPIN(cond, bar) do { unsigned _sp = 0; while (cond) { __builtin_amdgcn_s_sleep(1); \
;     if ((++_sp & 255u) == 0u) { if (xb_ld(&(bar)[XB_TMO])) break; if (_sp > XB_SPIN_CAP) { atomicAdd(&(bar)[XB_TMO], 1u); break; } } } } while (0)
; #define SEAM(k) do { if (IN(k) && hi > (k) + 1) xcd_barrier(xbar); } while (0)
; __device__ __forceinline__ void xcd_barrier(const XcdBarrier& b) {
;     asm volatile("s_waitcnt vmcnt(0)" ::: "memory");
;     __syncthreads();
;     if (threadIdx.x == 0) {
;         unsigned* bar = b.bar;
;         __builtin_amdgcn_s_waitcnt(0);
;         unsigned nloc = b.st[0], nx = b.st[1];
;         if (nloc == 0u) { xcd_barrier_complete(bar, b.x, nloc, nx); b.st[0] = nloc; b.st[1] = nx; }
;         const unsigned old = xb_add(&bar[XB_XSUB(b.x)], 1u);
;         const unsigned gen = old / nloc;
;         if (old + 1u == (gen + 1u) * nloc) {
;             __builtin_amdgcn_fence(__ATOMIC_RELEASE, "agent");
;             asm volatile("s_waitcnt vmcnt(0)" ::: "memory");
;             const unsigned og = xb_add(&bar[XB_TOP], 1u);
;             const unsigned tg = og / nx;
;             if (og + 1u == (tg + 1u) * nx) xb_add(&bar[XB_TOPGEN], 1u);
;             else XB_SPIN(xb_ld(&bar[XB_TOPGEN]) == tg, bar);
;             __builtin_amdgcn_fence(__ATOMIC_ACQUIRE, "agent");
;             xb_add(&bar[XB_XGEN(b.x)], 1u);
;             asm volatile("s_waitcnt vmcnt(0)" ::: "memory");
;         } else {
;             XB_SPIN(xb_ld(&bar[XB_XGEN(b.x)]) == gen, bar);
;             __builtin_amdgcn_fence(__ATOMIC_ACQUIRE, "agent");
;             asm volatile("s_waitcnt vmcnt(0)" ::: "memory");
;         }
;     }
;     __syncthreads();
; }
; __global__ void __launch_bounds__(NTHREADS, 2) mk_fwd(Params P) {
;     ...
;     SEAM(5);
.LBB0_448:
	s_cmp_gt_i32 s43, 6
	s_cselect_b64 s[4:5], -1, 0
	s_and_b64 s[0:1], s[0:1], s[4:5]
	s_andn2_b64 vcc, exec, s[0:1]
	s_cbranch_vccnz .LBB0_498
	s_waitcnt vmcnt(0)
	s_waitcnt vmcnt(0) lgkmcnt(0)
	s_barrier
	s_and_saveexec_b64 s[0:1], s[12:13]
	s_cbranch_execz .LBB0_497
	s_and_b32 s98, s2, 7
	s_lshl_b32 s98, s98, 2
	s_bfe_u32 s99, s2, 0x20003
	s_or_b32 s98, s98, s99
	s_lshl_b32 s98, s98, 6
	s_add_i32 s98, s98, 0xa400
	v_mov_b32_e32 v250, s98
	v_mov_b32_e32 v252, 1
	v_mov_b32_e32 v253, 0x2000c
	ds_read_b32 v254, v253
	s_waitcnt lgkmcnt(0)
	v_readfirstlane_b32 s99, v254
	s_cmp_eq_u32 s99, 1
	s_cbranch_scc1 .Lpb5_fast
	buffer_wbl2 sc1
	s_waitcnt vmcnt(0)
.Lpb5_fast:
	global_atomic_add v250, v252, s[54:55] offset:12
	v_mov_b32_e32 v253, 0xa140
	global_atomic_add v253, v252, s[54:55]
	v_mov_b32_e32 v253, 0x8200
	s_mov_b32 s99, 0
.Lpw5_spin:
	global_load_dword v251, v250, s[54:55] offset:12 sc1
	global_load_dword v254, v253, s[54:55] sc1
	s_waitcnt vmcnt(0)
	v_readfirstlane_b32 s98, v251
	s_cmp_ge_u32 s98, 8
	s_cbranch_scc0 .Lpw5_retry
	v_readfirstlane_b32 s98, v254
	s_cmp_ge_u32 s98, 8
	s_cbranch_scc1 .Lpw5_ok
.Lpw5_retry:
	s_sleep 1
	s_add_u32 s99, s99, 1
	s_cmp_lt_u32 s99, 0x40000
	s_cbranch_scc1 .Lpw5_spin

;     __device__ bool next(int i, Unit& u) const {
;         const long L = (long)i * G + c; if (L >= nwg) return false;
;         int wgid = (int)L; { const int q = nwg / NXCD, r = nwg % NXCD, xcd = wgid % NXCD, off = wgid / NXCD; wgid = (xcd < r ? xcd * (q + 1) : r * (q + 1) + (xcd - r) * q) + off; }
;         const int nig = WGM * nN, gid = wgid / nig, fm = gid * WGM, gsz = (nM - fm) < WGM ? (nM - fm) : WGM;
;         u.pm = fm + ((wgid % nig) % gsz); u.pn = (wgid % nig) / gsz; return true;
; __global__ void __launch_bounds__(NTHREADS, 2) mk_fwd(Params P) {
;     ...
;     if (IN(6)) {
;         pg8::Gemm g{SLOTA, WINB, MTOK, 8192, 2048, 1 << 30, 0}; pg8::StaticOrder S; S.init(MTOK, 8192, G, bid);
;         EpiL1In E{Qb, Kb, VTb, Zb, KPART}; pg8::gemm_phase<EpiL1In, true>(lds, g, S, E);
.LBB0_498:
	v_mov_b32_e32 v251, 0xa140
	global_load_dword v250, v251, s[54:55] sc1
	s_add_u32 s3, s40, 0x3c00000
	s_addc_u32 s76, s41, 0
	s_add_u32 s0, s40, 0xa000000
	s_addc_u32 s1, s41, 0
	s_cmp_lt_i32 s42, 7
	s_cselect_b64 s[6:7], -1, 0
	s_and_b64 s[16:17], s[6:7], s[4:5]
	s_andn2_b64 vcc, exec, s[16:17]
	s_cbranch_vccnz .LBB0_571
	s_cmpk_lt_i32 s2, 0x400
	s_cselect_b64 s[4:5], -1, 0
	s_cmpk_gt_i32 s2, 0x3ff
	v_readfirstlane_b32 s26, v164
	s_cbranch_scc1 .LBB0_505
	s_ashr_i32 s6, s2, 31
	s_lshr_b32 s6, s6, 29
	s_add_i32 s8, s2, s6
	s_and_b32 s6, s8, -8
	s_sub_i32 s9, s2, s6
	s_cmp_gt_i32 s9, -1
	s_cbranch_scc0 .LBB0_502
	s_lshl_b32 s10, s9, 7
	s_cbranch_execz .LBB0_503
	s_branch .LBB0_504

; __device__ __forceinline__ unsigned cvt_pk_bf16(float lo, float hi) { unsigned r; asm volatile("v_cvt_pk_bf16_f32 %0, %1, %2" : "=v"(r) : "v"(lo), "v"(hi)); return r; }
;     __device__ __forceinline__ void operator()(const Acc& acc, const Unit& u, int wr, int wc, int fr, int fq) const {
;         const int type = u.pn >> 3, cb = (u.pn & 7) * 256 + wc * 32 + 8 * fq;
;         if (type == 2) {
;             const int b = u.pm >> 3, sb = (u.pm & 7) * 256 + wr * 64;
;             const int pos = (fr < 4 || fr >= 12) ? fr : (fr < 8 ? fr + 4 : fr - 4);
; #pragma unroll
;             for (int bj = 0; bj < 2; ++bj)
; #pragma unroll
;                 for (int n = 0; n < 2; ++n)
; #pragma unroll
;                     for (int j = 0; j < 4; ++j) {
;                         const int c = cb + bj * 128 + 4 * n + j, h = c >> 7, d = c & 127;
;                         bf16_t* base = VT + ((size_t)((b * 16 + h) * 128 + d)) * SEQ + sb + pos;
; #pragma unroll
;                         for (int ai = 0; ai < 2; ++ai)
; #pragma unroll
;                             for (int m = 0; m < 4; ++m) base[ai * 128 + m * 16] = (bf16_t)(cvt_pk_bf16(acc[ai][bj][m][n][j], 0.f) & 0xffffu);
;                     }
;             return;
;         }
.LBB0_521:
	v_readfirstlane_b32 s98, v250
	s_cmp_ge_u32 s98, 0x100
	s_cbranch_scc1 .Lp6g_ok
	s_mov_b32 s99, 0
.Lp6g_spin:
	s_sleep 1
	global_load_dword v250, v251, s[54:55] sc1
	s_waitcnt vmcnt(0)
	v_readfirstlane_b32 s98, v250
	s_cmp_ge_u32 s98, 0x100
	s_cbranch_scc1 .Lp6g_ok
	s_add_u32 s99, s99, 1
	s_cmp_lt_u32 s99, 0x40000
	s_cbranch_scc1 .Lp6g_spin
